# MLA loop: row-max of the new scores moved under the PV MFMAs (one wave-serial VALU chain + LDS round trip off the critical path), on top of the single-path pipelined MLA loop, batched NA bias lookups,
# speedup vs baseline: 1.0127x; 1.0031x over previous
.LBB0_545:
	s_or_b64 exec, exec, s[6:7]
	v_add_f32_e32 v126, v144, v143
	v_add_f32_e32 v126, 0, v126
	v_add_f32_e32 v64, v145, v64
	v_add_f32_e32 v64, v64, v126
	v_add_f32_e32 v65, v146, v65
	v_add_f32_e32 v64, v65, v64
	v_add_f32_e32 v65, v147, v66
	v_add_f32_e32 v64, v65, v64
	v_add_f32_e32 v65, v157, v67
	v_add_f32_e32 v64, v65, v64
	v_add_f32_e32 v65, v158, v68
	v_add_f32_e32 v64, v65, v64
	v_add_f32_e32 v65, v159, v69
	v_add_f32_e32 v64, v65, v64
	v_add_f32_e32 v65, v160, v70
	v_add_f32_e32 v64, v65, v64
	v_add_f32_e32 v65, v161, v71
	v_add_f32_e32 v64, v65, v64
	v_add_f32_e32 v65, v162, v72
	v_add_f32_e32 v64, v65, v64
	v_add_f32_e32 v65, v163, v73
	v_add_f32_e32 v64, v65, v64
	v_add_f32_e32 v65, v164, v74
	v_add_f32_e32 v64, v65, v64
	v_add_f32_e32 v65, v165, v75
	v_add_f32_e32 v64, v65, v64
	v_add_f32_e32 v65, v166, v76
	v_add_f32_e32 v64, v65, v64
	v_add_f32_e32 v65, v167, v77
	v_add_f32_e32 v64, v65, v64
	v_add_f32_e32 v65, v79, v78
	v_add_f32_e32 v64, v65, v64
	v_add_f32_e32 v138, v138, v64
	v_add_u32_e32 v64, 0x80c0, v142
	v_ashrrev_i32_e32 v65, 31, v64
	v_lshlrev_b64 v[64:65], 10, v[64:65]
	v_lshl_add_u64 v[64:65], s[92:93], 0, v[64:65]
	v_lshl_add_u64 v[64:65], v[64:65], 0, s[68:69]
	v_lshl_add_u64 v[64:65], v[64:65], 0, v[98:99]
	global_load_dwordx4 v[126:129], v[64:65], off offset:128
	s_waitcnt lgkmcnt(0)
	s_barrier
	s_add_u32 s6, s92, s68
	s_addc_u32 s7, s93, 0
	v_lshl_add_u64 v[142:143], s[6:7], 0, v[98:99]
	v_lshl_add_u64 v[144:145], v[100:101], 1, s[26:27]
	v_add3_u32 v146, v152, s8, 64
	s_mov_b32 s1, 4
	v_xor_b32_e32 v64, 0x80000000, v139
	v_mov_b32_e32 v65, v64
	v_mov_b32_e32 v66, v64
	v_mov_b32_e32 v67, v64
	v_mov_b32_e32 v68, v64
	v_mov_b32_e32 v69, v64
	v_mov_b32_e32 v70, v64
	v_mov_b32_e32 v71, v64
	v_mov_b32_e32 v72, v64
	v_mov_b32_e32 v73, v64
	v_mov_b32_e32 v74, v64
	v_mov_b32_e32 v75, v64
	v_mov_b32_e32 v76, v64
	v_mov_b32_e32 v77, v64
	v_mov_b32_e32 v78, v64
	v_mov_b32_e32 v79, v64
	v_max3_f32 v100, v48, v49, v50
	v_max3_f32 v100, v100, v51, v52
	v_max3_f32 v100, v100, v53, v54
	v_max3_f32 v100, v100, v55, v56
	v_max3_f32 v100, v100, v57, v58
	v_max3_f32 v100, v100, v59, v60
	v_max3_f32 v100, v100, v61, v62
	v_max3_f32 v100, v100, v63, v63
	v_max3_f32 v98, v32, v33, v34
	v_max3_f32 v98, v98, v35, v36
	v_max3_f32 v98, v98, v37, v38
	v_max3_f32 v98, v98, v39, v40
	v_max3_f32 v98, v98, v41, v42
	v_max3_f32 v98, v98, v43, v44
	v_max3_f32 v98, v98, v45, v46
	v_max3_f32 v98, v98, v47, v47
	v_max3_f32 v100, v100, v98, v98
	ds_bpermute_b32 v98, v137, v100
	s_waitcnt lgkmcnt(0)
	v_max3_f32 v100, v100, v98, v100
.LBB0_546:
	s_nop 0
	v_cmp_lt_f32_e32 vcc, s78, v100
	s_cbranch_vccz .Lmla_norescale
	v_max_f32_e32 v100, v100, v100
	v_max_f32_e32 v100, 0, v100
	v_exp_f32_e64 v98, -v100
	v_add_f32_e32 v139, v139, v100
	v_pk_add_f32 v[48:49], v[48:49], v[100:101] op_sel_hi:[1,0] neg_lo:[0,1] neg_hi:[0,1]
	v_pk_add_f32 v[32:33], v[32:33], v[100:101] op_sel_hi:[1,0] neg_lo:[0,1] neg_hi:[0,1]
	v_mul_f32_e32 v138, v138, v98
	v_pk_add_f32 v[50:51], v[50:51], v[100:101] op_sel_hi:[1,0] neg_lo:[0,1] neg_hi:[0,1]
	v_pk_add_f32 v[34:35], v[34:35], v[100:101] op_sel_hi:[1,0] neg_lo:[0,1] neg_hi:[0,1]
	v_pk_add_f32 v[52:53], v[52:53], v[100:101] op_sel_hi:[1,0] neg_lo:[0,1] neg_hi:[0,1]
	v_pk_add_f32 v[36:37], v[36:37], v[100:101] op_sel_hi:[1,0] neg_lo:[0,1] neg_hi:[0,1]
	v_pk_add_f32 v[54:55], v[54:55], v[100:101] op_sel_hi:[1,0] neg_lo:[0,1] neg_hi:[0,1]
	v_pk_add_f32 v[38:39], v[38:39], v[100:101] op_sel_hi:[1,0] neg_lo:[0,1] neg_hi:[0,1]
	v_pk_add_f32 v[56:57], v[56:57], v[100:101] op_sel_hi:[1,0] neg_lo:[0,1] neg_hi:[0,1]
	v_pk_add_f32 v[40:41], v[40:41], v[100:101] op_sel_hi:[1,0] neg_lo:[0,1] neg_hi:[0,1]
	v_pk_add_f32 v[58:59], v[58:59], v[100:101] op_sel_hi:[1,0] neg_lo:[0,1] neg_hi:[0,1]
	v_pk_add_f32 v[42:43], v[42:43], v[100:101] op_sel_hi:[1,0] neg_lo:[0,1] neg_hi:[0,1]
	v_pk_add_f32 v[60:61], v[60:61], v[100:101] op_sel_hi:[1,0] neg_lo:[0,1] neg_hi:[0,1]
	v_pk_add_f32 v[44:45], v[44:45], v[100:101] op_sel_hi:[1,0] neg_lo:[0,1] neg_hi:[0,1]
	v_pk_add_f32 v[62:63], v[62:63], v[100:101] op_sel_hi:[1,0] neg_lo:[0,1] neg_hi:[0,1]
	v_pk_add_f32 v[46:47], v[46:47], v[100:101] op_sel_hi:[1,0] neg_lo:[0,1] neg_hi:[0,1]
	v_pk_mul_f32 v[30:31], v[30:31], v[98:99] op_sel_hi:[1,0]
	v_pk_mul_f32 v[28:29], v[28:29], v[98:99] op_sel_hi:[1,0]
	v_pk_mul_f32 v[26:27], v[26:27], v[98:99] op_sel_hi:[1,0]
	v_pk_mul_f32 v[24:25], v[24:25], v[98:99] op_sel_hi:[1,0]
	v_pk_mul_f32 v[22:23], v[22:23], v[98:99] op_sel_hi:[1,0]
	v_pk_mul_f32 v[20:21], v[20:21], v[98:99] op_sel_hi:[1,0]
	v_pk_mul_f32 v[18:19], v[18:19], v[98:99] op_sel_hi:[1,0]
	v_pk_mul_f32 v[16:17], v[16:17], v[98:99] op_sel_hi:[1,0]
	v_pk_mul_f32 v[14:15], v[14:15], v[98:99] op_sel_hi:[1,0]
	v_pk_mul_f32 v[12:13], v[12:13], v[98:99] op_sel_hi:[1,0]
	v_pk_mul_f32 v[10:11], v[10:11], v[98:99] op_sel_hi:[1,0]
	v_pk_mul_f32 v[8:9], v[8:9], v[98:99] op_sel_hi:[1,0]
	v_pk_mul_f32 v[6:7], v[6:7], v[98:99] op_sel_hi:[1,0]
	v_pk_mul_f32 v[4:5], v[4:5], v[98:99] op_sel_hi:[1,0]
	v_pk_mul_f32 v[2:3], v[2:3], v[98:99] op_sel_hi:[1,0]
	v_pk_mul_f32 v[0:1], v[0:1], v[98:99] op_sel_hi:[1,0]
	v_xor_b32_e32 v64, 0x80000000, v139
	v_mov_b32_e32 v65, v64
	v_mov_b32_e32 v66, v64
	v_mov_b32_e32 v67, v64
	v_mov_b32_e32 v68, v64
	v_mov_b32_e32 v69, v64
	v_mov_b32_e32 v70, v64
	v_mov_b32_e32 v71, v64
	v_mov_b32_e32 v72, v64
	v_mov_b32_e32 v73, v64
	v_mov_b32_e32 v74, v64
	v_mov_b32_e32 v75, v64
	v_mov_b32_e32 v76, v64
	v_mov_b32_e32 v77, v64
	v_mov_b32_e32 v78, v64
	v_mov_b32_e32 v79, v64
.Lmla_norescale:
	s_add_i32 s10, s1, -1
	s_and_b32 s11, s10, 1
	s_mul_i32 s7, s11, 0x3400
	v_add_u32_e32 v147, s7, v149
	ds_read_b128 v[110:113], v147
	ds_read_b128 v[114:117], v147 offset:32
	ds_read_b128 v[118:121], v147 offset:64
	ds_read_b128 v[152:155], v147 offset:96
	s_and_b32 s6, s1, 1
	v_exp_f32_e32 v141, v48
	v_exp_f32_e32 v157, v49
	v_exp_f32_e32 v158, v50
	v_exp_f32_e32 v159, v51
	v_exp_f32_e32 v160, v52
	v_exp_f32_e32 v161, v53
	v_exp_f32_e32 v162, v54
	v_exp_f32_e32 v163, v55
	v_exp_f32_e32 v164, v56
	v_exp_f32_e32 v165, v57
	v_exp_f32_e32 v166, v58
	v_exp_f32_e32 v167, v59
	v_exp_f32_e32 v168, v60
	v_exp_f32_e32 v169, v61
	v_exp_f32_e32 v170, v62
	v_exp_f32_e32 v171, v63
	s_waitcnt lgkmcnt(3)
	v_mfma_f32_32x32x16_bf16 v[48:63], v[110:113], v[106:109], v[64:79]
	ds_read_b128 v[234:237], v147 offset:128
	v_exp_f32_e32 v172, v32
	v_exp_f32_e32 v173, v33
	v_exp_f32_e32 v174, v34
	s_waitcnt lgkmcnt(3)
	v_mfma_f32_32x32x16_bf16 v[48:63], v[114:117], v[102:105], v[48:63]
	ds_read_b128 v[212:215], v147 offset:160
	v_exp_f32_e32 v175, v35
	v_exp_f32_e32 v176, v36
	v_exp_f32_e32 v177, v37
	s_waitcnt lgkmcnt(3)
	v_mfma_f32_32x32x16_bf16 v[48:63], v[118:121], v[92:95], v[48:63]
	ds_read_b128 v[216:219], v147 offset:6656
	v_exp_f32_e32 v178, v38
	v_exp_f32_e32 v179, v39
	v_exp_f32_e32 v187, v40
	s_waitcnt lgkmcnt(3)
	v_mfma_f32_32x32x16_bf16 v[48:63], v[152:155], v[88:91], v[48:63]
	ds_read_b128 v[238:241], v147 offset:6688
	v_exp_f32_e32 v188, v41
	v_exp_f32_e32 v189, v42
	v_exp_f32_e32 v190, v43
	s_waitcnt lgkmcnt(3)
	v_mfma_f32_32x32x16_bf16 v[48:63], v[234:237], v[84:87], v[48:63]
	ds_read_b128 v[242:245], v147 offset:6720
	v_exp_f32_e32 v191, v44
	v_exp_f32_e32 v192, v45
	v_exp_f32_e32 v193, v46
	s_waitcnt lgkmcnt(3)
	v_mfma_f32_32x32x16_bf16 v[48:63], v[212:215], v[80:83], v[48:63]
	ds_read_b128 v[246:249], v147 offset:6752
	v_exp_f32_e32 v194, v47
	v_cvt_pk_bf16_f32 v196, v141, v157
	v_cvt_pk_bf16_f32 v197, v158, v159
	s_waitcnt lgkmcnt(3)
	v_mfma_f32_32x32x16_bf16 v[32:47], v[216:219], v[106:109], v[64:79]
	ds_read_b128 v[110:113], v147 offset:6784
	v_cvt_pk_bf16_f32 v198, v160, v161
	v_cvt_pk_bf16_f32 v199, v162, v163
	v_cvt_pk_bf16_f32 v200, v164, v165
	s_waitcnt lgkmcnt(3)
	v_mfma_f32_32x32x16_bf16 v[32:47], v[238:241], v[102:105], v[32:47]
	ds_read_b128 v[114:117], v147 offset:6816
	v_cvt_pk_bf16_f32 v201, v166, v167
	v_cvt_pk_bf16_f32 v202, v168, v169
	v_cvt_pk_bf16_f32 v203, v170, v171
	s_waitcnt lgkmcnt(3)
	v_mfma_f32_32x32x16_bf16 v[32:47], v[242:245], v[92:95], v[32:47]
	s_mul_i32 s7, s6, 0x2400
	v_add_u32_e32 v156, s7, v97
	ds_read_b64_tr_b16 v[118:119], v156 offset:26624
	ds_read_b64_tr_b16 v[120:121], v156 offset:27776
	ds_read_b64_tr_b16 v[154:155], v156 offset:27840
	ds_read_b64_tr_b16 v[152:153], v156 offset:26688
	v_cvt_pk_bf16_f32 v204, v172, v173
	v_cvt_pk_bf16_f32 v205, v174, v175
	s_waitcnt lgkmcnt(6)
	v_mfma_f32_32x32x16_bf16 v[32:47], v[246:249], v[88:91], v[32:47]
	ds_read_b64_tr_b16 v[234:235], v156 offset:28928
	ds_read_b64_tr_b16 v[236:237], v156 offset:30080
	ds_read_b64_tr_b16 v[214:215], v156 offset:30144
	ds_read_b64_tr_b16 v[212:213], v156 offset:28992
	v_cvt_pk_bf16_f32 v206, v176, v177
	v_cvt_pk_bf16_f32 v207, v178, v179
	v_cvt_pk_bf16_f32 v208, v187, v188
	s_waitcnt lgkmcnt(9)
	v_mfma_f32_32x32x16_bf16 v[32:47], v[110:113], v[84:87], v[32:47]
	ds_read_b64_tr_b16 v[216:217], v156 offset:31232
	ds_read_b64_tr_b16 v[218:219], v156 offset:32384
	ds_read_b64_tr_b16 v[240:241], v156 offset:32448
	ds_read_b64_tr_b16 v[238:239], v156 offset:31296
	v_cvt_pk_bf16_f32 v209, v189, v190
	v_cvt_pk_bf16_f32 v210, v191, v192
	v_cvt_pk_bf16_f32 v211, v193, v194
	s_waitcnt lgkmcnt(12)
	v_mfma_f32_32x32x16_bf16 v[32:47], v[114:117], v[80:83], v[32:47]
	ds_read_b64_tr_b16 v[242:243], v156 offset:33536
	ds_read_b64_tr_b16 v[244:245], v156 offset:34688
	ds_read_b64_tr_b16 v[248:249], v156 offset:34752
	ds_read_b64_tr_b16 v[246:247], v156 offset:33600
	s_nop 1
	v_add_f32_e32 v195, v172, v141
	v_add_f32_e32 v195, 0, v195
	v_add_f32_e32 v101, v173, v157
	v_add_f32_e32 v195, v101, v195
	s_waitcnt lgkmcnt(14)
	v_mfma_f32_32x32x16_bf16 v[16:31], v[118:121], v[196:199], v[16:31]
	v_add_f32_e32 v101, v174, v158
	v_add_f32_e32 v195, v101, v195
	v_add_f32_e32 v101, v175, v159
	v_max3_f32 v100, v48, v49, v50
	v_max3_f32 v100, v100, v51, v52
	v_max3_f32 v100, v100, v53, v54
	s_waitcnt lgkmcnt(12)
	v_mfma_f32_32x32x16_bf16 v[0:15], v[152:155], v[196:199], v[0:15]
	s_mulk_i32 s6, 0x3400
	s_add_i32 s12, s6, 0
	v_add3_u32 v156, s12, v150, v134
	s_waitcnt vmcnt(1)
	ds_write_b128 v156, v[130:133]
	s_and_saveexec_b64 s[6:7], s[38:39]
	v_add3_u32 v156, s12, v151, v136
	ds_write_b128 v156, v[122:125] offset:128
	s_or_b64 exec, exec, s[6:7]
	v_add_f32_e32 v195, v101, v195
	v_add_f32_e32 v101, v176, v160
	v_max3_f32 v100, v100, v55, v56
	v_max3_f32 v100, v100, v57, v58
	s_waitcnt lgkmcnt(11)
	v_mfma_f32_32x32x16_bf16 v[16:31], v[234:237], v[200:203], v[16:31]
	v_add_f32_e32 v195, v101, v195
	v_add_f32_e32 v101, v177, v161
	v_add_f32_e32 v195, v101, v195
	v_max3_f32 v100, v100, v59, v60
	v_max3_f32 v100, v100, v61, v62
	v_max3_f32 v100, v100, v63, v63
	s_waitcnt lgkmcnt(9)
	v_mfma_f32_32x32x16_bf16 v[0:15], v[212:215], v[200:203], v[0:15]
	s_mulk_i32 s11, 0x2400
	v_add_u32_e32 v156, s11, v135
	v_add_u32_e32 v228, 64, v140
	s_waitcnt vmcnt(0)
	ds_write_b128 v156, v[126:129] offset:26624
	s_waitcnt lgkmcnt(8)
	v_mfma_f32_32x32x16_bf16 v[16:31], v[216:219], v[204:207], v[16:31]
	v_add_f32_e32 v101, v178, v162
	v_add_f32_e32 v195, v101, v195
	v_add_f32_e32 v101, v179, v163
	v_add_f32_e32 v195, v101, v195
	v_max3_f32 v98, v32, v33, v34
	v_max3_f32 v98, v98, v35, v36
	v_max3_f32 v98, v98, v37, v38
	s_waitcnt lgkmcnt(6)
	v_mfma_f32_32x32x16_bf16 v[0:15], v[238:241], v[204:207], v[0:15]
	s_cmpk_lt_u32 s10, 0x42
	s_cbranch_scc0 .Lmla_noload
	v_ashrrev_i32_e32 v229, 31, v228
	v_lshlrev_b64 v[220:221], 10, v[228:229]
	v_lshl_add_u64 v[220:221], v[142:143], 0, v[220:221]
	global_load_dwordx4 v[130:133], v[220:221], off
	s_and_saveexec_b64 s[6:7], s[38:39]
	s_cbranch_execz .Lmla_norr
	v_ashrrev_i32_e32 v147, 31, v146
	v_lshlrev_b64 v[220:221], 6, v[146:147]
	v_lshl_add_u64 v[220:221], v[144:145], 0, v[220:221]
	global_load_dwordx4 v[122:125], v[220:221], off

.Lmla_noload:
	v_ashrrev_i32_e32 v141, 31, v140
	v_lshlrev_b64 v[220:221], 10, v[140:141]
	v_lshl_add_u64 v[220:221], v[142:143], 0, v[220:221]
	global_load_dwordx4 v[126:129], v[220:221], off offset:128
	s_waitcnt lgkmcnt(4)
	v_mfma_f32_32x32x16_bf16 v[16:31], v[242:245], v[208:211], v[16:31]
	v_add_f32_e32 v101, v187, v164
	v_add_f32_e32 v195, v101, v195
	v_add_f32_e32 v101, v188, v165
	v_add_f32_e32 v195, v101, v195
	v_add_f32_e32 v101, v189, v166
	v_max3_f32 v98, v98, v39, v40
	v_max3_f32 v98, v98, v41, v42
	v_max3_f32 v98, v98, v43, v44
	s_waitcnt lgkmcnt(2)
	v_mfma_f32_32x32x16_bf16 v[0:15], v[246:249], v[208:211], v[0:15]
	v_max3_f32 v98, v98, v45, v46
	v_max3_f32 v98, v98, v47, v47
	v_max3_f32 v100, v100, v98, v98
	ds_bpermute_b32 v98, v137, v100
	v_add_f32_e32 v195, v101, v195
	v_add_f32_e32 v101, v190, v167
	v_add_f32_e32 v195, v101, v195
	v_add_f32_e32 v101, v191, v168
	v_add_f32_e32 v195, v101, v195
	v_add_f32_e32 v101, v192, v169
	v_add_f32_e32 v195, v101, v195
	v_add_f32_e32 v101, v193, v170
	v_add_f32_e32 v195, v101, v195
	v_add_f32_e32 v101, v194, v171
	v_add_f32_e32 v195, v101, v195
	v_add_f32_e32 v138, v138, v195
	s_waitcnt lgkmcnt(0)
	v_max3_f32 v100, v100, v98, v100
	s_barrier
	s_add_i32 s1, s1, 1
	v_add_u32_e32 v146, 64, v146
	s_cmpk_eq_i32 s1, 0x44
	s_cbranch_scc1 .LBB0_559
	v_mov_b32_e32 v140, v228
	s_branch .LBB0_546
